# code placement: one 4-byte pad behind the rewritten UP epilogue puts the FFN-down phase (K-loops + residual epilogue) back on the baseline's 8-byte instruction phase
# baseline (speedup 1.0000x reference)
;     __device__ __forceinline__ void operator()(const f32x4 (&acc)[2][2][4][2], const Unit& u, int wr, int wc, int fr, int fq) const {
;     ...
;         const int ch0 = 128 * u.pn + 32 * wc + 8 * fq;
;         f32x4 w0[2], w1[2], w2[2], bb[2];
; #pragma unroll
;         for (int bj = 0; bj < 2; ++bj) { const int col = bj * 2816 + ch0;
;             w0[bj] = *(const f32x4*)(cw + col); w1[bj] = *(const f32x4*)(cw + 5632 + col); w2[bj] = *(const f32x4*)(cw + 11264 + col); bb[bj] = *(const f32x4*)(cb + col); }
; #pragma unroll
;         for (int ai = 0; ai < 2; ++ai) { const int blk = ai * 2 + wr;
;             if (fr == 0) {
; #pragma unroll
;                 for (int bj = 0; bj < 2; ++bj)
; #pragma unroll
;                     for (int n = 0; n < 2; ++n) *(PG8_LAS f32x4*)(xb + ((((blk * 2 + 0) * 4 + wc) * 4 + fq) * 16 + (bj * 2 + n) * 4)) = acc[ai][bj][0][n]; }
;             if (fr == 15) {
; #pragma unroll
;                 for (int bj = 0; bj < 2; ++bj)
; #pragma unroll
;                     for (int n = 0; n < 2; ++n) *(PG8_LAS f32x4*)(xb + ((((blk * 2 + 1) * 4 + wc) * 4 + fq) * 16 + (bj * 2 + n) * 4)) = acc[ai][bj][3][n]; } }
;         asm volatile("s_waitcnt lgkmcnt(0)" ::: "memory"); __builtin_amdgcn_s_barrier(); asm volatile("" ::: "memory");
;     ...
;                 for (int m = 0; m < 4; ++m) { const int r = 128 * ai + 64 * wr + 16 * m + fr, t = tstart + r;
;                     const bool upok = t >= 1, dnok = (t + 1) < T, store_ok = (r >= vlo) && (r < vhi) && (t < T);
;                     f32x4 res[2];
; #pragma unroll
;                     for (int bj = 0; bj < 2; ++bj) { const f32x4 cur = acc[ai][bj][m][n];
;                         f32x4 su = cur, sd = cur;
;                         if (m > 0) { if (fr == 15) su = acc[ai][bj][m > 0 ? m - 1 : 0][n]; }
;                         if (m < 3) { if (fr == 0) sd = acc[ai][bj][m < 3 ? m + 1 : 3][n]; }
;                         f32x4 up, dn;
;                         up[0] = dpp_ror1(su[0]); up[1] = dpp_ror1(su[1]); up[2] = dpp_ror1(su[2]); up[3] = dpp_ror1(su[3]);
;                         dn[0] = dpp_ror15(sd[0]); dn[1] = dpp_ror15(sd[1]); dn[2] = dpp_ror15(sd[2]); dn[3] = dpp_ror15(sd[3]);
;                         if (m == 0) { f32x4 halo = zero4; if (blk > 0) halo = *(const PG8_LAS f32x4*)(xb + (((((blk - 1) * 2 + 1) * 4 + wc) * 4 + fq) * 16 + (bj * 2 + n) * 4)); if (fr == 0) up = halo; }
.LBB0_705:
	v_lshl_or_b32 v248, s2, 7, v229
	v_lshlrev_b32_e32 v247, 1, v248
	v_lshlrev_b32_e32 v248, 2, v248
	v_add_u32_e32 v249, 0x2c00, v248
	global_load_dwordx4 v[106:109], v248, s[62:63]
	global_load_dwordx4 v[110:113], v248, s[66:67]
	global_load_dwordx4 v[114:117], v248, s[68:69]
	global_load_dwordx4 v[118:121], v248, s[64:65]
	global_load_dwordx4 v[122:125], v249, s[62:63]
	global_load_dwordx4 v[126:129], v249, s[66:67]
	global_load_dwordx4 v[130:133], v249, s[68:69]
	global_load_dwordx4 v[134:137], v249, s[64:65]
	v_readlane_b32 s10, v254, 4
	v_readlane_b32 s11, v254, 5
	s_add_i32 s0, s78, s48
	s_mulk_i32 s0, 0x1600
	s_movk_i32 s29, 0x1600
	s_add_i32 s28, s93, -1
	v_add_u32_e32 v247, s0, v247
	v_mov_b32_e32 v202, 0
	v_mov_b32_e32 v203, 0
	v_and_b32_e32 v250, 7, v226
	v_lshlrev_b32_e32 v250, 3, v250
	v_add_u32_e32 v250, 0x27000, v250
	ds_write_b64 v250, v[202:203]
	s_mov_b64 exec, s[6:7]
	ds_write_b128 v238, v[166:169]
	ds_write_b128 v238, v[70:73] offset:16
	ds_write_b128 v238, v[162:165] offset:32
	ds_write_b128 v238, v[66:69] offset:48
	ds_write_b128 v239, v[102:105]
	ds_write_b128 v239, v[30:33] offset:16
	ds_write_b128 v239, v[98:101] offset:32
	ds_write_b128 v239, v[26:29] offset:48
	s_mov_b64 exec, s[4:5]
	ds_write_b128 v238, v[142:145] offset:1024
	ds_write_b128 v238, v[46:49] offset:1040
	ds_write_b128 v238, v[138:141] offset:1056
	ds_write_b128 v238, v[42:45] offset:1072
	ds_write_b128 v239, v[78:81] offset:1024
	ds_write_b128 v239, v[6:9] offset:1040
	ds_write_b128 v239, v[74:77] offset:1056
	ds_write_b128 v239, v[2:5] offset:1072
	s_mov_b64 exec, -1
	v_and_b32_e32 v250, 0xb80, v238
	v_lshlrev_b32_e32 v250, 3, v250
	v_bfe_u32 v251, v238, 6, 1
	v_lshl_add_u32 v250, v251, 3, v250
	v_lshl_add_u32 v250, v226, 4, v250
	v_add_u32_e32 v243, 0x20000, v250
	v_add_u32_e32 v244, 0xfffffff0, v243
	v_add_u32_e32 v250, 0xfffffc00, v238
	v_mov_b32_e32 v251, 0x27000
	v_cndmask_b32_e64 v245, v251, v250, s[74:75]
	v_add_u32_e32 v250, 0x800, v239
	v_cndmask_b32_e64 v246, v250, v251, s[74:75]
	s_waitcnt lgkmcnt(0)
	s_barrier
	s_cmp_lt_i32 s48, 1
	s_cbranch_scc1 .Lec_edge
	s_add_i32 s0, s48, 0x100
	s_cmp_ge_i32 s0, s93
	s_cbranch_scc1 .Lec_edge
	v_cmp_le_i32_e64 s[12:13], s54, v227
	v_cmp_gt_i32_e32 vcc, s55, v227
	s_and_b64 s[12:13], s[12:13], vcc
	v_cmp_le_i32_e64 s[14:15], s54, v231
	v_cmp_gt_i32_e32 vcc, s55, v231
	s_and_b64 s[14:15], s[14:15], vcc
	v_cmp_le_i32_e64 s[16:17], s54, v232
	v_cmp_gt_i32_e32 vcc, s55, v232
	s_and_b64 s[16:17], s[16:17], vcc
	v_cmp_le_i32_e64 s[18:19], s54, v233
	v_cmp_gt_i32_e32 vcc, s55, v233
	s_and_b64 s[18:19], s[18:19], vcc
	v_cmp_le_i32_e64 s[20:21], s54, v234
	v_cmp_gt_i32_e32 vcc, s55, v234
	s_and_b64 s[20:21], s[20:21], vcc
	v_cmp_le_i32_e64 s[22:23], s54, v235
	v_cmp_gt_i32_e32 vcc, s55, v235
	s_and_b64 s[22:23], s[22:23], vcc
	v_cmp_le_i32_e64 s[24:25], s54, v236
	v_cmp_gt_i32_e32 vcc, s55, v236
	s_and_b64 s[24:25], s[24:25], vcc
	v_cmp_le_i32_e64 s[26:27], s54, v237
	v_cmp_gt_i32_e32 vcc, s55, v237
	s_and_b64 s[26:27], s[26:27], vcc
	ds_write_b64 v243, v[166:167]
	ds_write_b64 v243, v[158:159] offset:256
	ds_write_b64 v243, v[150:151] offset:512
	ds_write_b64 v243, v[142:143] offset:768
	ds_read_b64 v[170:171], v244
	ds_read_b64 v[178:179], v243 offset:16
	ds_read_b64 v[198:199], v245
	ds_read_b64 v[172:173], v244 offset:256
	ds_read_b64 v[180:181], v243 offset:272
	ds_read_b64 v[174:175], v244 offset:512
	ds_read_b64 v[194:195], v243 offset:528
	ds_read_b64 v[176:177], v244 offset:768
	ds_read_b64 v[196:197], v243 offset:784
	ds_read_b64 v[200:201], v238 offset:2048
	s_waitcnt vmcnt(0)
	ds_write_b64 v243, v[168:169]
	ds_write_b64 v243, v[160:161] offset:256
	ds_write_b64 v243, v[152:153] offset:512
	ds_write_b64 v243, v[144:145] offset:768
	s_waitcnt lgkmcnt(11)
	v_cndmask_b32_e64 v170, v170, v198, s[6:7]
	v_cndmask_b32_e64 v171, v171, v199, s[6:7]
	v_pk_fma_f32 v[202:203], v[106:107], v[170:171], v[118:119]
	v_pk_fma_f32 v[166:167], v[166:167], v[110:111], v[202:203]
	v_pk_fma_f32 v[166:167], v[114:115], v[178:179], v[166:167]
	ds_read_b64 v[170:171], v244
	ds_read_b64 v[178:179], v243 offset:16
	ds_read_b64 v[198:199], v245 offset:8
	s_waitcnt lgkmcnt(12)
	v_pk_fma_f32 v[202:203], v[106:107], v[172:173], v[118:119]
	v_pk_fma_f32 v[158:159], v[158:159], v[110:111], v[202:203]
	v_pk_fma_f32 v[158:159], v[114:115], v[180:181], v[158:159]
	ds_read_b64 v[172:173], v244 offset:256
	ds_read_b64 v[180:181], v243 offset:272
	s_waitcnt lgkmcnt(12)
	v_pk_fma_f32 v[202:203], v[106:107], v[174:175], v[118:119]
	v_pk_fma_f32 v[150:151], v[150:151], v[110:111], v[202:203]
	v_pk_fma_f32 v[150:151], v[114:115], v[194:195], v[150:151]
	ds_read_b64 v[174:175], v244 offset:512
	ds_read_b64 v[194:195], v243 offset:528
	s_waitcnt lgkmcnt(11)
	v_cndmask_b32_e64 v196, v196, v200, s[4:5]
	v_cndmask_b32_e64 v197, v197, v201, s[4:5]
	v_pk_fma_f32 v[202:203], v[106:107], v[176:177], v[118:119]
	v_pk_fma_f32 v[142:143], v[142:143], v[110:111], v[202:203]
	v_pk_fma_f32 v[142:143], v[114:115], v[196:197], v[142:143]
	ds_read_b64 v[176:177], v244 offset:768
	ds_read_b64 v[196:197], v243 offset:784
	ds_read_b64 v[200:201], v238 offset:2056
	ds_write_b64 v243, v[162:163]
	ds_write_b64 v243, v[154:155] offset:256
	ds_write_b64 v243, v[146:147] offset:512
	ds_write_b64 v243, v[138:139] offset:768
	s_waitcnt lgkmcnt(11)
	v_cndmask_b32_e64 v170, v170, v198, s[6:7]
	v_cndmask_b32_e64 v171, v171, v199, s[6:7]
	v_pk_fma_f32 v[202:203], v[108:109], v[170:171], v[120:121]
	v_pk_fma_f32 v[168:169], v[168:169], v[112:113], v[202:203]
	v_pk_fma_f32 v[168:169], v[116:117], v[178:179], v[168:169]
	ds_read_b64 v[170:171], v244
	ds_read_b64 v[178:179], v243 offset:16
	ds_read_b64 v[198:199], v245 offset:32
	s_waitcnt lgkmcnt(12)
; #define PG8_LAS __attribute__((address_space(3)))
; __device__ __forceinline__ unsigned cvt_pk_bf16(float lo, float hi) { unsigned r; asm volatile("v_cvt_pk_bf16_f32 %0, %1, %2" : "=v"(r) : "v"(lo), "v"(hi)); return r; }
;     __device__ __forceinline__ void operator()(const f32x4 (&acc)[2][2][4][2], const Unit& u, int wr, int wc, int fr, int fq) const {
;     ...
;                 for (int m = 0; m < 4; ++m) { const int r = 128 * ai + 64 * wr + 16 * m + fr, t = tstart + r;
;                     const bool upok = t >= 1, dnok = (t + 1) < T, store_ok = (r >= vlo) && (r < vhi) && (t < T);
;                     f32x4 res[2];
; #pragma unroll
;                     for (int bj = 0; bj < 2; ++bj) { const f32x4 cur = acc[ai][bj][m][n];
;                         f32x4 su = cur, sd = cur;
;                         if (m > 0) { if (fr == 15) su = acc[ai][bj][m > 0 ? m - 1 : 0][n]; }
;                         if (m < 3) { if (fr == 0) sd = acc[ai][bj][m < 3 ? m + 1 : 3][n]; }
;                         f32x4 up, dn;
;                         up[0] = dpp_ror1(su[0]); up[1] = dpp_ror1(su[1]); up[2] = dpp_ror1(su[2]); up[3] = dpp_ror1(su[3]);
;                         dn[0] = dpp_ror15(sd[0]); dn[1] = dpp_ror15(sd[1]); dn[2] = dpp_ror15(sd[2]); dn[3] = dpp_ror15(sd[3]);
;                         if (m == 0) { f32x4 halo = zero4; if (blk > 0) halo = *(const PG8_LAS f32x4*)(xb + (((((blk - 1) * 2 + 1) * 4 + wc) * 4 + fq) * 16 + (bj * 2 + n) * 4)); if (fr == 0) up = halo; }
;                         if (m == 3) { f32x4 halo = zero4; if (blk < 3) halo = *(const PG8_LAS f32x4*)(xb + (((((blk + 1) * 2 + 0) * 4 + wc) * 4 + fq) * 16 + (bj * 2 + n) * 4)); if (fr == 15) dn = halo; }
;                         if (edge) { if (!upok) up = zero4; if (!dnok) dn = zero4; }
;                         res[bj] = bb[bj] + w0[bj] * up + w1[bj] * cur + w2[bj] * dn; }
;                     if (store_ok) {
;                         float o[4];
; #pragma unroll
;                         for (int j = 0; j < 4; ++j) { const float gg = res[1][j]; o[j] = gg * __builtin_amdgcn_rcpf(1.f + __expf(-gg)) * res[0][j]; }
;                         u32x2 w; w.x = cvt_pk_bf16(o[0], o[1]); w.y = cvt_pk_bf16(o[2], o[3]);
;                         *(u32x2*)(ACT + (size_t)(seqrow + t) * 2816 + ch0 + 4 * n) = w; } } }
	v_pk_fma_f32 v[202:203], v[108:109], v[172:173], v[120:121]
	v_pk_fma_f32 v[160:161], v[160:161], v[112:113], v[202:203]
	v_pk_fma_f32 v[160:161], v[116:117], v[180:181], v[160:161]
	ds_read_b64 v[172:173], v244 offset:256
	ds_read_b64 v[180:181], v243 offset:272
	s_waitcnt lgkmcnt(12)
	v_pk_fma_f32 v[202:203], v[108:109], v[174:175], v[120:121]
	v_pk_fma_f32 v[152:153], v[152:153], v[112:113], v[202:203]
	v_pk_fma_f32 v[152:153], v[116:117], v[194:195], v[152:153]
	ds_read_b64 v[174:175], v244 offset:512
	ds_read_b64 v[194:195], v243 offset:528
	s_waitcnt lgkmcnt(11)
	v_cndmask_b32_e64 v196, v196, v200, s[4:5]
	v_cndmask_b32_e64 v197, v197, v201, s[4:5]
	v_pk_fma_f32 v[202:203], v[108:109], v[176:177], v[120:121]
	v_pk_fma_f32 v[144:145], v[144:145], v[112:113], v[202:203]
	v_pk_fma_f32 v[144:145], v[116:117], v[196:197], v[144:145]
	ds_read_b64 v[176:177], v244 offset:768
	ds_read_b64 v[196:197], v243 offset:784
	ds_read_b64 v[200:201], v238 offset:2080
	ds_write_b64 v243, v[164:165]
	ds_write_b64 v243, v[156:157] offset:256
	ds_write_b64 v243, v[148:149] offset:512
	ds_write_b64 v243, v[140:141] offset:768
	s_waitcnt lgkmcnt(11)
	v_cndmask_b32_e64 v170, v170, v198, s[6:7]
	v_cndmask_b32_e64 v171, v171, v199, s[6:7]
	v_pk_fma_f32 v[202:203], v[122:123], v[170:171], v[134:135]
	v_pk_fma_f32 v[162:163], v[162:163], v[126:127], v[202:203]
	v_pk_fma_f32 v[162:163], v[130:131], v[178:179], v[162:163]
	ds_read_b64 v[170:171], v244
	ds_read_b64 v[178:179], v243 offset:16
	ds_read_b64 v[198:199], v245 offset:40
	s_waitcnt lgkmcnt(12)
	v_pk_fma_f32 v[202:203], v[122:123], v[172:173], v[134:135]
	v_pk_fma_f32 v[154:155], v[154:155], v[126:127], v[202:203]
	v_pk_fma_f32 v[154:155], v[130:131], v[180:181], v[154:155]
	ds_read_b64 v[172:173], v244 offset:256
	ds_read_b64 v[180:181], v243 offset:272
	s_waitcnt lgkmcnt(12)
	v_pk_fma_f32 v[202:203], v[122:123], v[174:175], v[134:135]
	v_pk_fma_f32 v[146:147], v[146:147], v[126:127], v[202:203]
	v_pk_fma_f32 v[146:147], v[130:131], v[194:195], v[146:147]
	ds_read_b64 v[174:175], v244 offset:512
	ds_read_b64 v[194:195], v243 offset:528
	s_waitcnt lgkmcnt(11)
	v_cndmask_b32_e64 v196, v196, v200, s[4:5]
	v_cndmask_b32_e64 v197, v197, v201, s[4:5]
	v_pk_fma_f32 v[202:203], v[122:123], v[176:177], v[134:135]
	v_pk_fma_f32 v[138:139], v[138:139], v[126:127], v[202:203]
	v_pk_fma_f32 v[138:139], v[130:131], v[196:197], v[138:139]
	ds_read_b64 v[176:177], v244 offset:768
	ds_read_b64 v[196:197], v243 offset:784
	ds_read_b64 v[200:201], v238 offset:2088
	ds_write_b64 v243, v[102:103]
	ds_write_b64 v243, v[94:95] offset:256
	ds_write_b64 v243, v[86:87] offset:512
	ds_write_b64 v243, v[78:79] offset:768
	s_waitcnt lgkmcnt(11)
	v_cndmask_b32_e64 v170, v170, v198, s[6:7]
	v_cndmask_b32_e64 v171, v171, v199, s[6:7]
	v_pk_fma_f32 v[202:203], v[124:125], v[170:171], v[136:137]
	v_pk_fma_f32 v[164:165], v[164:165], v[128:129], v[202:203]
	v_pk_fma_f32 v[164:165], v[132:133], v[178:179], v[164:165]
	ds_read_b64 v[170:171], v244
	ds_read_b64 v[178:179], v243 offset:16
	ds_read_b64 v[198:199], v238 offset:3072
	s_waitcnt lgkmcnt(12)
	v_pk_fma_f32 v[202:203], v[124:125], v[172:173], v[136:137]
	v_pk_fma_f32 v[156:157], v[156:157], v[128:129], v[202:203]
	v_pk_fma_f32 v[156:157], v[132:133], v[180:181], v[156:157]
	ds_read_b64 v[172:173], v244 offset:256
	ds_read_b64 v[180:181], v243 offset:272
	s_waitcnt lgkmcnt(12)
	v_pk_fma_f32 v[202:203], v[124:125], v[174:175], v[136:137]
	v_pk_fma_f32 v[148:149], v[148:149], v[128:129], v[202:203]
	v_pk_fma_f32 v[148:149], v[132:133], v[194:195], v[148:149]
	ds_read_b64 v[174:175], v244 offset:512
	ds_read_b64 v[194:195], v243 offset:528
	s_waitcnt lgkmcnt(11)
	v_cndmask_b32_e64 v196, v196, v200, s[4:5]
	v_cndmask_b32_e64 v197, v197, v201, s[4:5]
	v_pk_fma_f32 v[202:203], v[124:125], v[176:177], v[136:137]
	v_pk_fma_f32 v[140:141], v[140:141], v[128:129], v[202:203]
	v_pk_fma_f32 v[140:141], v[132:133], v[196:197], v[140:141]
	ds_read_b64 v[176:177], v244 offset:768
	ds_read_b64 v[196:197], v243 offset:784
	ds_read_b64 v[200:201], v246
	v_mul_f32_e32 v208, 0xbfb8aa3b, v162
	v_mul_f32_e32 v209, 0xbfb8aa3b, v163
	v_mul_f32_e32 v210, 0xbfb8aa3b, v164
	v_mul_f32_e32 v211, 0xbfb8aa3b, v165
	v_exp_f32_e32 v208, v208
	v_exp_f32_e32 v209, v209
	v_exp_f32_e32 v210, v210
	v_exp_f32_e32 v211, v211
	v_add_f32_e32 v208, 1.0, v208
	v_add_f32_e32 v209, 1.0, v209
	v_add_f32_e32 v210, 1.0, v210
	v_add_f32_e32 v211, 1.0, v211
	v_rcp_f32_e32 v208, v208
	v_rcp_f32_e32 v209, v209
	v_rcp_f32_e32 v210, v210
	v_rcp_f32_e32 v211, v211
	v_mul_f32_e32 v162, v162, v208
	v_mul_f32_e32 v163, v163, v209
	v_mul_f32_e32 v164, v164, v210
	v_mul_f32_e32 v165, v165, v211
	v_mul_f32_e32 v162, v166, v162
	v_mul_f32_e32 v163, v167, v163
	v_mul_f32_e32 v164, v168, v164
	v_mul_f32_e32 v165, v169, v165
	v_cvt_pk_bf16_f32 v212, v162, v163
	v_cvt_pk_bf16_f32 v213, v164, v165
	v_mad_u32_u24 v221, v227, s29, v247
	s_and_saveexec_b64 s[30:31], s[12:13]
	global_store_dwordx2 v221, v[212:213], s[10:11]
	s_mov_b64 exec, s[30:31]
	v_mul_f32_e32 v208, 0xbfb8aa3b, v154
	v_mul_f32_e32 v209, 0xbfb8aa3b, v155
	v_mul_f32_e32 v210, 0xbfb8aa3b, v156
	v_mul_f32_e32 v211, 0xbfb8aa3b, v157
	v_exp_f32_e32 v208, v208
	v_exp_f32_e32 v209, v209
	v_exp_f32_e32 v210, v210
	v_exp_f32_e32 v211, v211
	v_add_f32_e32 v208, 1.0, v208
	v_add_f32_e32 v209, 1.0, v209
	v_add_f32_e32 v210, 1.0, v210
	v_add_f32_e32 v211, 1.0, v211
	v_rcp_f32_e32 v208, v208
	v_rcp_f32_e32 v209, v209
	v_rcp_f32_e32 v210, v210
	v_rcp_f32_e32 v211, v211
	v_mul_f32_e32 v154, v154, v208
	v_mul_f32_e32 v155, v155, v209
	v_mul_f32_e32 v156, v156, v210
	v_mul_f32_e32 v157, v157, v211
; #define PG8_LAS __attribute__((address_space(3)))
;     __device__ __forceinline__ void operator()(const f32x4 (&acc)[2][2][4][2], const Unit& u, int wr, int wc, int fr, int fq) const {
;     ...
;         for (int n = 0; n < 2; ++n) {
;             if (n == 1) {
; #pragma unroll
;                 for (int bj = 0; bj < 2; ++bj) { const int col = bj * 2816 + ch0 + 4;
;                     w0[bj] = *(const f32x4*)(cw + col); w1[bj] = *(const f32x4*)(cw + 5632 + col); w2[bj] = *(const f32x4*)(cw + 11264 + col); bb[bj] = *(const f32x4*)(cb + col); } }
; #pragma unroll
;             for (int ai = 0; ai < 2; ++ai) { const int blk = ai * 2 + wr;
; #pragma unroll
;                 for (int m = 0; m < 4; ++m) { const int r = 128 * ai + 64 * wr + 16 * m + fr, t = tstart + r;
;                     const bool upok = t >= 1, dnok = (t + 1) < T, store_ok = (r >= vlo) && (r < vhi) && (t < T);
;                     f32x4 res[2];
; #pragma unroll
;                     for (int bj = 0; bj < 2; ++bj) { const f32x4 cur = acc[ai][bj][m][n];
;                         f32x4 su = cur, sd = cur;
;                         if (m > 0) { if (fr == 15) su = acc[ai][bj][m > 0 ? m - 1 : 0][n]; }
;                         if (m < 3) { if (fr == 0) sd = acc[ai][bj][m < 3 ? m + 1 : 3][n]; }
;                         f32x4 up, dn;
;                         up[0] = dpp_ror1(su[0]); up[1] = dpp_ror1(su[1]); up[2] = dpp_ror1(su[2]); up[3] = dpp_ror1(su[3]);
;                         dn[0] = dpp_ror15(sd[0]); dn[1] = dpp_ror15(sd[1]); dn[2] = dpp_ror15(sd[2]); dn[3] = dpp_ror15(sd[3]);
;                         if (m == 0) { f32x4 halo = zero4; if (blk > 0) halo = *(const PG8_LAS f32x4*)(xb + (((((blk - 1) * 2 + 1) * 4 + wc) * 4 + fq) * 16 + (bj * 2 + n) * 4)); if (fr == 0) up = halo; }
;                         if (m == 3) { f32x4 halo = zero4; if (blk < 3) halo = *(const PG8_LAS f32x4*)(xb + (((((blk + 1) * 2 + 0) * 4 + wc) * 4 + fq) * 16 + (bj * 2 + n) * 4)); if (fr == 15) dn = halo; }
;                         if (edge) { if (!upok) up = zero4; if (!dnok) dn = zero4; }
;                         res[bj] = bb[bj] + w0[bj] * up + w1[bj] * cur + w2[bj] * dn; }
;                     if (store_ok) {
;                         float o[4];
; #pragma unroll
;                         for (int j = 0; j < 4; ++j) { const float gg = res[1][j]; o[j] = gg * __builtin_amdgcn_rcpf(1.f + __expf(-gg)) * res[0][j]; }
	v_mul_f32_e32 v154, v158, v154
	v_mul_f32_e32 v155, v159, v155
	v_mul_f32_e32 v156, v160, v156
	v_mul_f32_e32 v157, v161, v157
	v_cvt_pk_bf16_f32 v218, v154, v155
	v_cvt_pk_bf16_f32 v219, v156, v157
	v_mad_u32_u24 v40, v231, s29, v247
	s_and_saveexec_b64 s[30:31], s[14:15]
	global_store_dwordx2 v40, v[218:219], s[10:11]
	s_mov_b64 exec, s[30:31]
	v_mul_f32_e32 v208, 0xbfb8aa3b, v146
	v_mul_f32_e32 v209, 0xbfb8aa3b, v147
	v_mul_f32_e32 v210, 0xbfb8aa3b, v148
	v_mul_f32_e32 v211, 0xbfb8aa3b, v149
	v_exp_f32_e32 v208, v208
	v_exp_f32_e32 v209, v209
	v_exp_f32_e32 v210, v210
	v_exp_f32_e32 v211, v211
	v_add_f32_e32 v208, 1.0, v208
	v_add_f32_e32 v209, 1.0, v209
	v_add_f32_e32 v210, 1.0, v210
	v_add_f32_e32 v211, 1.0, v211
	v_rcp_f32_e32 v208, v208
	v_rcp_f32_e32 v209, v209
	v_rcp_f32_e32 v210, v210
	v_rcp_f32_e32 v211, v211
	v_mul_f32_e32 v146, v146, v208
	v_mul_f32_e32 v147, v147, v209
	v_mul_f32_e32 v148, v148, v210
	v_mul_f32_e32 v149, v149, v211
	v_mul_f32_e32 v146, v150, v146
	v_mul_f32_e32 v147, v151, v147
	v_mul_f32_e32 v148, v152, v148
	v_mul_f32_e32 v149, v153, v149
	v_cvt_pk_bf16_f32 v212, v146, v147
	v_cvt_pk_bf16_f32 v213, v148, v149
	v_mad_u32_u24 v221, v232, s29, v247
	s_and_saveexec_b64 s[30:31], s[16:17]
	global_store_dwordx2 v221, v[212:213], s[10:11]
	s_mov_b64 exec, s[30:31]
	v_mul_f32_e32 v208, 0xbfb8aa3b, v138
	v_mul_f32_e32 v209, 0xbfb8aa3b, v139
	v_mul_f32_e32 v210, 0xbfb8aa3b, v140
	v_mul_f32_e32 v211, 0xbfb8aa3b, v141
	v_exp_f32_e32 v208, v208
	v_exp_f32_e32 v209, v209
	v_exp_f32_e32 v210, v210
	v_exp_f32_e32 v211, v211
	v_add_f32_e32 v208, 1.0, v208
	v_add_f32_e32 v209, 1.0, v209
	v_add_f32_e32 v210, 1.0, v210
	v_add_f32_e32 v211, 1.0, v211
	v_rcp_f32_e32 v208, v208
	v_rcp_f32_e32 v209, v209
	v_rcp_f32_e32 v210, v210
	v_rcp_f32_e32 v211, v211
	v_mul_f32_e32 v138, v138, v208
	v_mul_f32_e32 v139, v139, v209
	v_mul_f32_e32 v140, v140, v210
	v_mul_f32_e32 v141, v141, v211
	v_mul_f32_e32 v138, v142, v138
	v_mul_f32_e32 v139, v143, v139
	v_mul_f32_e32 v140, v144, v140
	v_mul_f32_e32 v141, v145, v141
	v_cvt_pk_bf16_f32 v218, v138, v139
	v_cvt_pk_bf16_f32 v219, v140, v141
	v_mad_u32_u24 v40, v233, s29, v247
	s_and_saveexec_b64 s[30:31], s[18:19]
	global_store_dwordx2 v40, v[218:219], s[10:11]
	s_mov_b64 exec, s[30:31]
	global_load_dwordx4 v[138:141], v248, s[62:63] offset:16
	global_load_dwordx4 v[142:145], v248, s[66:67] offset:16
	global_load_dwordx4 v[146:149], v248, s[68:69] offset:16
	global_load_dwordx4 v[150:153], v248, s[64:65] offset:16
	global_load_dwordx4 v[154:157], v249, s[62:63] offset:16
	global_load_dwordx4 v[158:161], v249, s[66:67] offset:16
	global_load_dwordx4 v[162:165], v249, s[68:69] offset:16
	global_load_dwordx4 v[166:169], v249, s[64:65] offset:16
	ds_write_b64 v243, v[104:105]
	ds_write_b64 v243, v[96:97] offset:256
	ds_write_b64 v243, v[88:89] offset:512
	ds_write_b64 v243, v[80:81] offset:768
	s_waitcnt lgkmcnt(11)
	v_cndmask_b32_e64 v170, v170, v198, s[6:7]
	v_cndmask_b32_e64 v171, v171, v199, s[6:7]
	v_pk_fma_f32 v[202:203], v[106:107], v[170:171], v[118:119]
	v_pk_fma_f32 v[102:103], v[102:103], v[110:111], v[202:203]
	v_pk_fma_f32 v[102:103], v[114:115], v[178:179], v[102:103]
	ds_read_b64 v[170:171], v244
	ds_read_b64 v[178:179], v243 offset:16
	ds_read_b64 v[198:199], v238 offset:3080
	s_waitcnt lgkmcnt(12)
	v_pk_fma_f32 v[202:203], v[106:107], v[172:173], v[118:119]
	v_pk_fma_f32 v[94:95], v[94:95], v[110:111], v[202:203]
	v_pk_fma_f32 v[94:95], v[114:115], v[180:181], v[94:95]
	ds_read_b64 v[172:173], v244 offset:256
	ds_read_b64 v[180:181], v243 offset:272
	s_waitcnt lgkmcnt(12)
	v_pk_fma_f32 v[202:203], v[106:107], v[174:175], v[118:119]
	v_pk_fma_f32 v[86:87], v[86:87], v[110:111], v[202:203]
	v_pk_fma_f32 v[86:87], v[114:115], v[194:195], v[86:87]
	ds_read_b64 v[174:175], v244 offset:512
	ds_read_b64 v[194:195], v243 offset:528
	s_waitcnt lgkmcnt(11)
	v_cndmask_b32_e64 v196, v196, v200, s[4:5]
	v_cndmask_b32_e64 v197, v197, v201, s[4:5]
	v_pk_fma_f32 v[202:203], v[106:107], v[176:177], v[118:119]
	v_pk_fma_f32 v[78:79], v[78:79], v[110:111], v[202:203]
	v_pk_fma_f32 v[78:79], v[114:115], v[196:197], v[78:79]
	ds_read_b64 v[176:177], v244 offset:768
	ds_read_b64 v[196:197], v243 offset:784
	ds_read_b64 v[200:201], v246 offset:8
	ds_write_b64 v243, v[98:99]
	ds_write_b64 v243, v[90:91] offset:256
	ds_write_b64 v243, v[82:83] offset:512
	ds_write_b64 v243, v[74:75] offset:768
	s_waitcnt lgkmcnt(11)
	v_cndmask_b32_e64 v170, v170, v198, s[6:7]
	v_cndmask_b32_e64 v171, v171, v199, s[6:7]
	v_pk_fma_f32 v[202:203], v[108:109], v[170:171], v[120:121]
	v_pk_fma_f32 v[104:105], v[104:105], v[112:113], v[202:203]
	v_pk_fma_f32 v[104:105], v[116:117], v[178:179], v[104:105]
	ds_read_b64 v[170:171], v244
	ds_read_b64 v[178:179], v243 offset:16
	ds_read_b64 v[198:199], v238 offset:3104
	s_waitcnt lgkmcnt(12)
	v_pk_fma_f32 v[202:203], v[108:109], v[172:173], v[120:121]
	v_pk_fma_f32 v[96:97], v[96:97], v[112:113], v[202:203]
	v_pk_fma_f32 v[96:97], v[116:117], v[180:181], v[96:97]
	ds_read_b64 v[172:173], v244 offset:256
	ds_read_b64 v[180:181], v243 offset:272
	s_waitcnt lgkmcnt(12)
	v_pk_fma_f32 v[202:203], v[108:109], v[174:175], v[120:121]
	v_pk_fma_f32 v[88:89], v[88:89], v[112:113], v[202:203]
	v_pk_fma_f32 v[88:89], v[116:117], v[194:195], v[88:89]
	ds_read_b64 v[174:175], v244 offset:512
	ds_read_b64 v[194:195], v243 offset:528
	s_waitcnt lgkmcnt(11)
; #define PG8_LAS __attribute__((address_space(3)))
; __device__ __forceinline__ unsigned cvt_pk_bf16(float lo, float hi) { unsigned r; asm volatile("v_cvt_pk_bf16_f32 %0, %1, %2" : "=v"(r) : "v"(lo), "v"(hi)); return r; }
;     __device__ __forceinline__ void operator()(const f32x4 (&acc)[2][2][4][2], const Unit& u, int wr, int wc, int fr, int fq) const {
;     ...
;                 for (int m = 0; m < 4; ++m) { const int r = 128 * ai + 64 * wr + 16 * m + fr, t = tstart + r;
;                     const bool upok = t >= 1, dnok = (t + 1) < T, store_ok = (r >= vlo) && (r < vhi) && (t < T);
;                     f32x4 res[2];
; #pragma unroll
;                     for (int bj = 0; bj < 2; ++bj) { const f32x4 cur = acc[ai][bj][m][n];
;                         f32x4 su = cur, sd = cur;
;                         if (m > 0) { if (fr == 15) su = acc[ai][bj][m > 0 ? m - 1 : 0][n]; }
;                         if (m < 3) { if (fr == 0) sd = acc[ai][bj][m < 3 ? m + 1 : 3][n]; }
;                         f32x4 up, dn;
;                         up[0] = dpp_ror1(su[0]); up[1] = dpp_ror1(su[1]); up[2] = dpp_ror1(su[2]); up[3] = dpp_ror1(su[3]);
;                         dn[0] = dpp_ror15(sd[0]); dn[1] = dpp_ror15(sd[1]); dn[2] = dpp_ror15(sd[2]); dn[3] = dpp_ror15(sd[3]);
;                         if (m == 0) { f32x4 halo = zero4; if (blk > 0) halo = *(const PG8_LAS f32x4*)(xb + (((((blk - 1) * 2 + 1) * 4 + wc) * 4 + fq) * 16 + (bj * 2 + n) * 4)); if (fr == 0) up = halo; }
;                         if (m == 3) { f32x4 halo = zero4; if (blk < 3) halo = *(const PG8_LAS f32x4*)(xb + (((((blk + 1) * 2 + 0) * 4 + wc) * 4 + fq) * 16 + (bj * 2 + n) * 4)); if (fr == 15) dn = halo; }
;                         if (edge) { if (!upok) up = zero4; if (!dnok) dn = zero4; }
;                         res[bj] = bb[bj] + w0[bj] * up + w1[bj] * cur + w2[bj] * dn; }
;                     if (store_ok) {
;                         float o[4];
; #pragma unroll
;                         for (int j = 0; j < 4; ++j) { const float gg = res[1][j]; o[j] = gg * __builtin_amdgcn_rcpf(1.f + __expf(-gg)) * res[0][j]; }
;                         u32x2 w; w.x = cvt_pk_bf16(o[0], o[1]); w.y = cvt_pk_bf16(o[2], o[3]);
;                         *(u32x2*)(ACT + (size_t)(seqrow + t) * 2816 + ch0 + 4 * n) = w; } } }
	v_cndmask_b32_e64 v196, v196, v200, s[4:5]
	v_cndmask_b32_e64 v197, v197, v201, s[4:5]
	v_pk_fma_f32 v[202:203], v[108:109], v[176:177], v[120:121]
	v_pk_fma_f32 v[80:81], v[80:81], v[112:113], v[202:203]
	v_pk_fma_f32 v[80:81], v[116:117], v[196:197], v[80:81]
	ds_read_b64 v[176:177], v244 offset:768
	ds_read_b64 v[196:197], v243 offset:784
	ds_read_b64 v[200:201], v246 offset:32
	ds_write_b64 v243, v[100:101]
	ds_write_b64 v243, v[92:93] offset:256
	ds_write_b64 v243, v[84:85] offset:512
	ds_write_b64 v243, v[76:77] offset:768
	s_waitcnt lgkmcnt(11)
	v_cndmask_b32_e64 v170, v170, v198, s[6:7]
	v_cndmask_b32_e64 v171, v171, v199, s[6:7]
	v_pk_fma_f32 v[202:203], v[122:123], v[170:171], v[134:135]
	v_pk_fma_f32 v[98:99], v[98:99], v[126:127], v[202:203]
	v_pk_fma_f32 v[98:99], v[130:131], v[178:179], v[98:99]
	ds_read_b64 v[170:171], v244
	ds_read_b64 v[178:179], v243 offset:16
	ds_read_b64 v[198:199], v238 offset:3112
	s_waitcnt lgkmcnt(12)
	v_pk_fma_f32 v[202:203], v[122:123], v[172:173], v[134:135]
	v_pk_fma_f32 v[90:91], v[90:91], v[126:127], v[202:203]
	v_pk_fma_f32 v[90:91], v[130:131], v[180:181], v[90:91]
	ds_read_b64 v[172:173], v244 offset:256
	ds_read_b64 v[180:181], v243 offset:272
	s_waitcnt lgkmcnt(12)
	v_pk_fma_f32 v[202:203], v[122:123], v[174:175], v[134:135]
	v_pk_fma_f32 v[82:83], v[82:83], v[126:127], v[202:203]
	v_pk_fma_f32 v[82:83], v[130:131], v[194:195], v[82:83]
	ds_read_b64 v[174:175], v244 offset:512
	ds_read_b64 v[194:195], v243 offset:528
	s_waitcnt lgkmcnt(11)
	v_cndmask_b32_e64 v196, v196, v200, s[4:5]
	v_cndmask_b32_e64 v197, v197, v201, s[4:5]
	v_pk_fma_f32 v[202:203], v[122:123], v[176:177], v[134:135]
	v_pk_fma_f32 v[74:75], v[74:75], v[126:127], v[202:203]
	v_pk_fma_f32 v[74:75], v[130:131], v[196:197], v[74:75]
	ds_read_b64 v[176:177], v244 offset:768
	ds_read_b64 v[196:197], v243 offset:784
	ds_read_b64 v[200:201], v246 offset:40
	ds_write_b64 v243, v[70:71]
	ds_write_b64 v243, v[62:63] offset:256
	ds_write_b64 v243, v[54:55] offset:512
	ds_write_b64 v243, v[46:47] offset:768
	s_waitcnt lgkmcnt(11)
	v_cndmask_b32_e64 v170, v170, v198, s[6:7]
	v_cndmask_b32_e64 v171, v171, v199, s[6:7]
	v_pk_fma_f32 v[202:203], v[124:125], v[170:171], v[136:137]
	v_pk_fma_f32 v[100:101], v[100:101], v[128:129], v[202:203]
	v_pk_fma_f32 v[100:101], v[132:133], v[178:179], v[100:101]
	ds_read_b64 v[170:171], v244
	ds_read_b64 v[178:179], v243 offset:16
	ds_read_b64 v[198:199], v245 offset:16
	s_waitcnt lgkmcnt(12)
	v_pk_fma_f32 v[202:203], v[124:125], v[172:173], v[136:137]
	v_pk_fma_f32 v[92:93], v[92:93], v[128:129], v[202:203]
	v_pk_fma_f32 v[92:93], v[132:133], v[180:181], v[92:93]
	ds_read_b64 v[172:173], v244 offset:256
	ds_read_b64 v[180:181], v243 offset:272
	s_waitcnt lgkmcnt(12)
	v_pk_fma_f32 v[202:203], v[124:125], v[174:175], v[136:137]
	v_pk_fma_f32 v[84:85], v[84:85], v[128:129], v[202:203]
	v_pk_fma_f32 v[84:85], v[132:133], v[194:195], v[84:85]
	ds_read_b64 v[174:175], v244 offset:512
	ds_read_b64 v[194:195], v243 offset:528
	s_waitcnt lgkmcnt(11)
	v_cndmask_b32_e64 v196, v196, v200, s[4:5]
	v_cndmask_b32_e64 v197, v197, v201, s[4:5]
	v_pk_fma_f32 v[202:203], v[124:125], v[176:177], v[136:137]
	v_pk_fma_f32 v[76:77], v[76:77], v[128:129], v[202:203]
	v_pk_fma_f32 v[76:77], v[132:133], v[196:197], v[76:77]
	ds_read_b64 v[176:177], v244 offset:768
	ds_read_b64 v[196:197], v243 offset:784
	ds_read_b64 v[200:201], v238 offset:2064
	v_mul_f32_e32 v208, 0xbfb8aa3b, v98
	v_mul_f32_e32 v209, 0xbfb8aa3b, v99
	v_mul_f32_e32 v210, 0xbfb8aa3b, v100
	v_mul_f32_e32 v211, 0xbfb8aa3b, v101
	v_exp_f32_e32 v208, v208
	v_exp_f32_e32 v209, v209
	v_exp_f32_e32 v210, v210
	v_exp_f32_e32 v211, v211
	v_add_f32_e32 v208, 1.0, v208
	v_add_f32_e32 v209, 1.0, v209
	v_add_f32_e32 v210, 1.0, v210
	v_add_f32_e32 v211, 1.0, v211
	v_rcp_f32_e32 v208, v208
	v_rcp_f32_e32 v209, v209
	v_rcp_f32_e32 v210, v210
	v_rcp_f32_e32 v211, v211
	v_mul_f32_e32 v98, v98, v208
	v_mul_f32_e32 v99, v99, v209
	v_mul_f32_e32 v100, v100, v210
	v_mul_f32_e32 v101, v101, v211
	v_mul_f32_e32 v98, v102, v98
	v_mul_f32_e32 v99, v103, v99
	v_mul_f32_e32 v100, v104, v100
	v_mul_f32_e32 v101, v105, v101
	v_cvt_pk_bf16_f32 v212, v98, v99
	v_cvt_pk_bf16_f32 v213, v100, v101
	v_mad_u32_u24 v221, v234, s29, v247
	s_and_saveexec_b64 s[30:31], s[20:21]
	global_store_dwordx2 v221, v[212:213], s[10:11]
	s_mov_b64 exec, s[30:31]
	v_mul_f32_e32 v208, 0xbfb8aa3b, v90
	v_mul_f32_e32 v209, 0xbfb8aa3b, v91
	v_mul_f32_e32 v210, 0xbfb8aa3b, v92
	v_mul_f32_e32 v211, 0xbfb8aa3b, v93
	v_exp_f32_e32 v208, v208
	v_exp_f32_e32 v209, v209
	v_exp_f32_e32 v210, v210
	v_exp_f32_e32 v211, v211
	v_add_f32_e32 v208, 1.0, v208
	v_add_f32_e32 v209, 1.0, v209
	v_add_f32_e32 v210, 1.0, v210
	v_add_f32_e32 v211, 1.0, v211
	v_rcp_f32_e32 v208, v208
	v_rcp_f32_e32 v209, v209
	v_rcp_f32_e32 v210, v210
	v_rcp_f32_e32 v211, v211
	v_mul_f32_e32 v90, v90, v208
	v_mul_f32_e32 v91, v91, v209
	v_mul_f32_e32 v92, v92, v210
	v_mul_f32_e32 v93, v93, v211
	v_mul_f32_e32 v90, v94, v90
	v_mul_f32_e32 v91, v95, v91
	v_mul_f32_e32 v92, v96, v92
	v_mul_f32_e32 v93, v97, v93
	v_cvt_pk_bf16_f32 v218, v90, v91
	v_cvt_pk_bf16_f32 v219, v92, v93
	v_mad_u32_u24 v40, v235, s29, v247
	s_and_saveexec_b64 s[30:31], s[22:23]
	global_store_dwordx2 v40, v[218:219], s[10:11]
	s_mov_b64 exec, s[30:31]
	v_mul_f32_e32 v208, 0xbfb8aa3b, v82
	v_mul_f32_e32 v209, 0xbfb8aa3b, v83
	v_mul_f32_e32 v210, 0xbfb8aa3b, v84
	v_mul_f32_e32 v211, 0xbfb8aa3b, v85
	v_exp_f32_e32 v208, v208
	v_exp_f32_e32 v209, v209
	v_exp_f32_e32 v210, v210
	v_exp_f32_e32 v211, v211
	v_add_f32_e32 v208, 1.0, v208
	v_add_f32_e32 v209, 1.0, v209
	v_add_f32_e32 v210, 1.0, v210
; #define PG8_LAS __attribute__((address_space(3)))
;     __device__ __forceinline__ void operator()(const f32x4 (&acc)[2][2][4][2], const Unit& u, int wr, int wc, int fr, int fq) const {
;     ...
;         for (int n = 0; n < 2; ++n) {
;             if (n == 1) {
; #pragma unroll
;                 for (int bj = 0; bj < 2; ++bj) { const int col = bj * 2816 + ch0 + 4;
;                     w0[bj] = *(const f32x4*)(cw + col); w1[bj] = *(const f32x4*)(cw + 5632 + col); w2[bj] = *(const f32x4*)(cw + 11264 + col); bb[bj] = *(const f32x4*)(cb + col); } }
; #pragma unroll
;             for (int ai = 0; ai < 2; ++ai) { const int blk = ai * 2 + wr;
; #pragma unroll
;                 for (int m = 0; m < 4; ++m) { const int r = 128 * ai + 64 * wr + 16 * m + fr, t = tstart + r;
;                     const bool upok = t >= 1, dnok = (t + 1) < T, store_ok = (r >= vlo) && (r < vhi) && (t < T);
;                     f32x4 res[2];
; #pragma unroll
;                     for (int bj = 0; bj < 2; ++bj) { const f32x4 cur = acc[ai][bj][m][n];
;                         f32x4 su = cur, sd = cur;
;                         if (m > 0) { if (fr == 15) su = acc[ai][bj][m > 0 ? m - 1 : 0][n]; }
;                         if (m < 3) { if (fr == 0) sd = acc[ai][bj][m < 3 ? m + 1 : 3][n]; }
;                         f32x4 up, dn;
;                         up[0] = dpp_ror1(su[0]); up[1] = dpp_ror1(su[1]); up[2] = dpp_ror1(su[2]); up[3] = dpp_ror1(su[3]);
;                         dn[0] = dpp_ror15(sd[0]); dn[1] = dpp_ror15(sd[1]); dn[2] = dpp_ror15(sd[2]); dn[3] = dpp_ror15(sd[3]);
;                         if (m == 0) { f32x4 halo = zero4; if (blk > 0) halo = *(const PG8_LAS f32x4*)(xb + (((((blk - 1) * 2 + 1) * 4 + wc) * 4 + fq) * 16 + (bj * 2 + n) * 4)); if (fr == 0) up = halo; }
;                         if (m == 3) { f32x4 halo = zero4; if (blk < 3) halo = *(const PG8_LAS f32x4*)(xb + (((((blk + 1) * 2 + 0) * 4 + wc) * 4 + fq) * 16 + (bj * 2 + n) * 4)); if (fr == 15) dn = halo; }
;                         if (edge) { if (!upok) up = zero4; if (!dnok) dn = zero4; }
;                         res[bj] = bb[bj] + w0[bj] * up + w1[bj] * cur + w2[bj] * dn; }
;                     if (store_ok) {
;                         float o[4];
; #pragma unroll
;                         for (int j = 0; j < 4; ++j) { const float gg = res[1][j]; o[j] = gg * __builtin_amdgcn_rcpf(1.f + __expf(-gg)) * res[0][j]; }
	v_add_f32_e32 v211, 1.0, v211
	v_rcp_f32_e32 v208, v208
	v_rcp_f32_e32 v209, v209
	v_rcp_f32_e32 v210, v210
	v_rcp_f32_e32 v211, v211
	v_mul_f32_e32 v82, v82, v208
	v_mul_f32_e32 v83, v83, v209
	v_mul_f32_e32 v84, v84, v210
	v_mul_f32_e32 v85, v85, v211
	v_mul_f32_e32 v82, v86, v82
	v_mul_f32_e32 v83, v87, v83
	v_mul_f32_e32 v84, v88, v84
	v_mul_f32_e32 v85, v89, v85
	v_cvt_pk_bf16_f32 v212, v82, v83
	v_cvt_pk_bf16_f32 v213, v84, v85
	v_mad_u32_u24 v221, v236, s29, v247
	s_and_saveexec_b64 s[30:31], s[24:25]
	global_store_dwordx2 v221, v[212:213], s[10:11]
	s_mov_b64 exec, s[30:31]
	v_mul_f32_e32 v208, 0xbfb8aa3b, v74
	v_mul_f32_e32 v209, 0xbfb8aa3b, v75
	v_mul_f32_e32 v210, 0xbfb8aa3b, v76
	v_mul_f32_e32 v211, 0xbfb8aa3b, v77
	v_exp_f32_e32 v208, v208
	v_exp_f32_e32 v209, v209
	v_exp_f32_e32 v210, v210
	v_exp_f32_e32 v211, v211
	v_add_f32_e32 v208, 1.0, v208
	v_add_f32_e32 v209, 1.0, v209
	v_add_f32_e32 v210, 1.0, v210
	v_add_f32_e32 v211, 1.0, v211
	v_rcp_f32_e32 v208, v208
	v_rcp_f32_e32 v209, v209
	v_rcp_f32_e32 v210, v210
	v_rcp_f32_e32 v211, v211
	v_mul_f32_e32 v74, v74, v208
	v_mul_f32_e32 v75, v75, v209
	v_mul_f32_e32 v76, v76, v210
	v_mul_f32_e32 v77, v77, v211
	v_mul_f32_e32 v74, v78, v74
	v_mul_f32_e32 v75, v79, v75
	v_mul_f32_e32 v76, v80, v76
	v_mul_f32_e32 v77, v81, v77
	v_cvt_pk_bf16_f32 v218, v74, v75
	v_cvt_pk_bf16_f32 v219, v76, v77
	v_mad_u32_u24 v40, v237, s29, v247
	s_and_saveexec_b64 s[30:31], s[26:27]
	global_store_dwordx2 v40, v[218:219], s[10:11]
	s_mov_b64 exec, s[30:31]
	s_waitcnt vmcnt(4)
	ds_write_b64 v243, v[72:73]
	ds_write_b64 v243, v[64:65] offset:256
	ds_write_b64 v243, v[56:57] offset:512
	ds_write_b64 v243, v[48:49] offset:768
	s_waitcnt lgkmcnt(11)
	v_cndmask_b32_e64 v170, v170, v198, s[6:7]
	v_cndmask_b32_e64 v171, v171, v199, s[6:7]
	v_pk_fma_f32 v[202:203], v[138:139], v[170:171], v[150:151]
	v_pk_fma_f32 v[70:71], v[70:71], v[142:143], v[202:203]
	v_pk_fma_f32 v[70:71], v[146:147], v[178:179], v[70:71]
	ds_read_b64 v[170:171], v244
	ds_read_b64 v[178:179], v243 offset:16
	ds_read_b64 v[198:199], v245 offset:24
	s_waitcnt lgkmcnt(12)
	v_pk_fma_f32 v[202:203], v[138:139], v[172:173], v[150:151]
	v_pk_fma_f32 v[62:63], v[62:63], v[142:143], v[202:203]
	v_pk_fma_f32 v[62:63], v[146:147], v[180:181], v[62:63]
	ds_read_b64 v[172:173], v244 offset:256
	ds_read_b64 v[180:181], v243 offset:272
	s_waitcnt lgkmcnt(12)
	v_pk_fma_f32 v[202:203], v[138:139], v[174:175], v[150:151]
	v_pk_fma_f32 v[54:55], v[54:55], v[142:143], v[202:203]
	v_pk_fma_f32 v[54:55], v[146:147], v[194:195], v[54:55]
	ds_read_b64 v[174:175], v244 offset:512
	ds_read_b64 v[194:195], v243 offset:528
	s_waitcnt lgkmcnt(11)
	v_cndmask_b32_e64 v196, v196, v200, s[4:5]
	v_cndmask_b32_e64 v197, v197, v201, s[4:5]
	v_pk_fma_f32 v[202:203], v[138:139], v[176:177], v[150:151]
	v_pk_fma_f32 v[46:47], v[46:47], v[142:143], v[202:203]
	v_pk_fma_f32 v[46:47], v[146:147], v[196:197], v[46:47]
	ds_read_b64 v[176:177], v244 offset:768
	ds_read_b64 v[196:197], v243 offset:784
	ds_read_b64 v[200:201], v238 offset:2072
	ds_write_b64 v243, v[66:67]
	ds_write_b64 v243, v[58:59] offset:256
	ds_write_b64 v243, v[50:51] offset:512
	ds_write_b64 v243, v[42:43] offset:768
	s_waitcnt lgkmcnt(11)
	v_cndmask_b32_e64 v170, v170, v198, s[6:7]
	v_cndmask_b32_e64 v171, v171, v199, s[6:7]
	v_pk_fma_f32 v[202:203], v[140:141], v[170:171], v[152:153]
	v_pk_fma_f32 v[72:73], v[72:73], v[144:145], v[202:203]
	v_pk_fma_f32 v[72:73], v[148:149], v[178:179], v[72:73]
	ds_read_b64 v[170:171], v244
	ds_read_b64 v[178:179], v243 offset:16
	ds_read_b64 v[198:199], v245 offset:48
	s_waitcnt lgkmcnt(12)
	v_pk_fma_f32 v[202:203], v[140:141], v[172:173], v[152:153]
	v_pk_fma_f32 v[64:65], v[64:65], v[144:145], v[202:203]
	v_pk_fma_f32 v[64:65], v[148:149], v[180:181], v[64:65]
	ds_read_b64 v[172:173], v244 offset:256
	ds_read_b64 v[180:181], v243 offset:272
	s_waitcnt lgkmcnt(12)
	v_pk_fma_f32 v[202:203], v[140:141], v[174:175], v[152:153]
	v_pk_fma_f32 v[56:57], v[56:57], v[144:145], v[202:203]
	v_pk_fma_f32 v[56:57], v[148:149], v[194:195], v[56:57]
	ds_read_b64 v[174:175], v244 offset:512
	ds_read_b64 v[194:195], v243 offset:528
	s_waitcnt lgkmcnt(11)
	v_cndmask_b32_e64 v196, v196, v200, s[4:5]
	v_cndmask_b32_e64 v197, v197, v201, s[4:5]
	v_pk_fma_f32 v[202:203], v[140:141], v[176:177], v[152:153]
	v_pk_fma_f32 v[48:49], v[48:49], v[144:145], v[202:203]
	v_pk_fma_f32 v[48:49], v[148:149], v[196:197], v[48:49]
	ds_read_b64 v[176:177], v244 offset:768
	ds_read_b64 v[196:197], v243 offset:784
	ds_read_b64 v[200:201], v238 offset:2096
	ds_write_b64 v243, v[68:69]
	ds_write_b64 v243, v[60:61] offset:256
	ds_write_b64 v243, v[52:53] offset:512
	ds_write_b64 v243, v[44:45] offset:768
	s_waitcnt lgkmcnt(11)
	v_cndmask_b32_e64 v170, v170, v198, s[6:7]
	v_cndmask_b32_e64 v171, v171, v199, s[6:7]
	v_pk_fma_f32 v[202:203], v[154:155], v[170:171], v[166:167]
	v_pk_fma_f32 v[66:67], v[66:67], v[158:159], v[202:203]
	v_pk_fma_f32 v[66:67], v[162:163], v[178:179], v[66:67]
	ds_read_b64 v[170:171], v244
	ds_read_b64 v[178:179], v243 offset:16
	ds_read_b64 v[198:199], v245 offset:56
	s_waitcnt lgkmcnt(12)
	v_pk_fma_f32 v[202:203], v[154:155], v[172:173], v[166:167]
	v_pk_fma_f32 v[58:59], v[58:59], v[158:159], v[202:203]
	v_pk_fma_f32 v[58:59], v[162:163], v[180:181], v[58:59]
	ds_read_b64 v[172:173], v244 offset:256
	ds_read_b64 v[180:181], v243 offset:272
	s_waitcnt lgkmcnt(12)
	v_pk_fma_f32 v[202:203], v[154:155], v[174:175], v[166:167]
	v_pk_fma_f32 v[50:51], v[50:51], v[158:159], v[202:203]
	v_pk_fma_f32 v[50:51], v[162:163], v[194:195], v[50:51]
	ds_read_b64 v[174:175], v244 offset:512
	ds_read_b64 v[194:195], v243 offset:528
	s_waitcnt lgkmcnt(11)
; #define PG8_LAS __attribute__((address_space(3)))
; __device__ __forceinline__ unsigned cvt_pk_bf16(float lo, float hi) { unsigned r; asm volatile("v_cvt_pk_bf16_f32 %0, %1, %2" : "=v"(r) : "v"(lo), "v"(hi)); return r; }
;     __device__ __forceinline__ void operator()(const f32x4 (&acc)[2][2][4][2], const Unit& u, int wr, int wc, int fr, int fq) const {
;     ...
;                 for (int m = 0; m < 4; ++m) { const int r = 128 * ai + 64 * wr + 16 * m + fr, t = tstart + r;
;                     const bool upok = t >= 1, dnok = (t + 1) < T, store_ok = (r >= vlo) && (r < vhi) && (t < T);
;                     f32x4 res[2];
; #pragma unroll
;                     for (int bj = 0; bj < 2; ++bj) { const f32x4 cur = acc[ai][bj][m][n];
;                         f32x4 su = cur, sd = cur;
;                         if (m > 0) { if (fr == 15) su = acc[ai][bj][m > 0 ? m - 1 : 0][n]; }
;                         if (m < 3) { if (fr == 0) sd = acc[ai][bj][m < 3 ? m + 1 : 3][n]; }
;                         f32x4 up, dn;
;                         up[0] = dpp_ror1(su[0]); up[1] = dpp_ror1(su[1]); up[2] = dpp_ror1(su[2]); up[3] = dpp_ror1(su[3]);
;                         dn[0] = dpp_ror15(sd[0]); dn[1] = dpp_ror15(sd[1]); dn[2] = dpp_ror15(sd[2]); dn[3] = dpp_ror15(sd[3]);
;                         if (m == 0) { f32x4 halo = zero4; if (blk > 0) halo = *(const PG8_LAS f32x4*)(xb + (((((blk - 1) * 2 + 1) * 4 + wc) * 4 + fq) * 16 + (bj * 2 + n) * 4)); if (fr == 0) up = halo; }
;                         if (m == 3) { f32x4 halo = zero4; if (blk < 3) halo = *(const PG8_LAS f32x4*)(xb + (((((blk + 1) * 2 + 0) * 4 + wc) * 4 + fq) * 16 + (bj * 2 + n) * 4)); if (fr == 15) dn = halo; }
;                         if (edge) { if (!upok) up = zero4; if (!dnok) dn = zero4; }
;                         res[bj] = bb[bj] + w0[bj] * up + w1[bj] * cur + w2[bj] * dn; }
;                     if (store_ok) {
;                         float o[4];
; #pragma unroll
;                         for (int j = 0; j < 4; ++j) { const float gg = res[1][j]; o[j] = gg * __builtin_amdgcn_rcpf(1.f + __expf(-gg)) * res[0][j]; }
;                         u32x2 w; w.x = cvt_pk_bf16(o[0], o[1]); w.y = cvt_pk_bf16(o[2], o[3]);
;                         *(u32x2*)(ACT + (size_t)(seqrow + t) * 2816 + ch0 + 4 * n) = w; } } }
	v_cndmask_b32_e64 v196, v196, v200, s[4:5]
	v_cndmask_b32_e64 v197, v197, v201, s[4:5]
	v_pk_fma_f32 v[202:203], v[154:155], v[176:177], v[166:167]
	v_pk_fma_f32 v[42:43], v[42:43], v[158:159], v[202:203]
	v_pk_fma_f32 v[42:43], v[162:163], v[196:197], v[42:43]
	ds_read_b64 v[176:177], v244 offset:768
	ds_read_b64 v[196:197], v243 offset:784
	ds_read_b64 v[200:201], v238 offset:2104
	ds_write_b64 v243, v[30:31]
	ds_write_b64 v243, v[22:23] offset:256
	ds_write_b64 v243, v[14:15] offset:512
	ds_write_b64 v243, v[6:7] offset:768
	s_waitcnt lgkmcnt(11)
	v_cndmask_b32_e64 v170, v170, v198, s[6:7]
	v_cndmask_b32_e64 v171, v171, v199, s[6:7]
	v_pk_fma_f32 v[202:203], v[156:157], v[170:171], v[168:169]
	v_pk_fma_f32 v[68:69], v[68:69], v[160:161], v[202:203]
	v_pk_fma_f32 v[68:69], v[164:165], v[178:179], v[68:69]
	ds_read_b64 v[170:171], v244
	ds_read_b64 v[178:179], v243 offset:16
	ds_read_b64 v[198:199], v238 offset:3088
	s_waitcnt lgkmcnt(12)
	v_pk_fma_f32 v[202:203], v[156:157], v[172:173], v[168:169]
	v_pk_fma_f32 v[60:61], v[60:61], v[160:161], v[202:203]
	v_pk_fma_f32 v[60:61], v[164:165], v[180:181], v[60:61]
	ds_read_b64 v[172:173], v244 offset:256
	ds_read_b64 v[180:181], v243 offset:272
	s_waitcnt lgkmcnt(12)
	v_pk_fma_f32 v[202:203], v[156:157], v[174:175], v[168:169]
	v_pk_fma_f32 v[52:53], v[52:53], v[160:161], v[202:203]
	v_pk_fma_f32 v[52:53], v[164:165], v[194:195], v[52:53]
	ds_read_b64 v[174:175], v244 offset:512
	ds_read_b64 v[194:195], v243 offset:528
	s_waitcnt lgkmcnt(11)
	v_cndmask_b32_e64 v196, v196, v200, s[4:5]
	v_cndmask_b32_e64 v197, v197, v201, s[4:5]
	v_pk_fma_f32 v[202:203], v[156:157], v[176:177], v[168:169]
	v_pk_fma_f32 v[44:45], v[44:45], v[160:161], v[202:203]
	v_pk_fma_f32 v[44:45], v[164:165], v[196:197], v[44:45]
	ds_read_b64 v[176:177], v244 offset:768
	ds_read_b64 v[196:197], v243 offset:784
	ds_read_b64 v[200:201], v246 offset:16
	v_mul_f32_e32 v208, 0xbfb8aa3b, v66
	v_mul_f32_e32 v209, 0xbfb8aa3b, v67
	v_mul_f32_e32 v210, 0xbfb8aa3b, v68
	v_mul_f32_e32 v211, 0xbfb8aa3b, v69
	v_exp_f32_e32 v208, v208
	v_exp_f32_e32 v209, v209
	v_exp_f32_e32 v210, v210
	v_exp_f32_e32 v211, v211
	v_add_f32_e32 v208, 1.0, v208
	v_add_f32_e32 v209, 1.0, v209
	v_add_f32_e32 v210, 1.0, v210
	v_add_f32_e32 v211, 1.0, v211
	v_rcp_f32_e32 v208, v208
	v_rcp_f32_e32 v209, v209
	v_rcp_f32_e32 v210, v210
	v_rcp_f32_e32 v211, v211
	v_mul_f32_e32 v66, v66, v208
	v_mul_f32_e32 v67, v67, v209
	v_mul_f32_e32 v68, v68, v210
	v_mul_f32_e32 v69, v69, v211
	v_mul_f32_e32 v66, v70, v66
	v_mul_f32_e32 v67, v71, v67
	v_mul_f32_e32 v68, v72, v68
	v_mul_f32_e32 v69, v73, v69
	v_cvt_pk_bf16_f32 v212, v66, v67
	v_cvt_pk_bf16_f32 v213, v68, v69
	v_mad_u32_u24 v221, v227, s29, v247
	s_and_saveexec_b64 s[30:31], s[12:13]
	global_store_dwordx2 v221, v[212:213], s[10:11] offset:8
	s_mov_b64 exec, s[30:31]
	v_mul_f32_e32 v208, 0xbfb8aa3b, v58
	v_mul_f32_e32 v209, 0xbfb8aa3b, v59
	v_mul_f32_e32 v210, 0xbfb8aa3b, v60
	v_mul_f32_e32 v211, 0xbfb8aa3b, v61
	v_exp_f32_e32 v208, v208
	v_exp_f32_e32 v209, v209
	v_exp_f32_e32 v210, v210
	v_exp_f32_e32 v211, v211
	v_add_f32_e32 v208, 1.0, v208
	v_add_f32_e32 v209, 1.0, v209
	v_add_f32_e32 v210, 1.0, v210
	v_add_f32_e32 v211, 1.0, v211
	v_rcp_f32_e32 v208, v208
	v_rcp_f32_e32 v209, v209
	v_rcp_f32_e32 v210, v210
	v_rcp_f32_e32 v211, v211
	v_mul_f32_e32 v58, v58, v208
	v_mul_f32_e32 v59, v59, v209
	v_mul_f32_e32 v60, v60, v210
	v_mul_f32_e32 v61, v61, v211
	v_mul_f32_e32 v58, v62, v58
	v_mul_f32_e32 v59, v63, v59
	v_mul_f32_e32 v60, v64, v60
	v_mul_f32_e32 v61, v65, v61
	v_cvt_pk_bf16_f32 v218, v58, v59
	v_cvt_pk_bf16_f32 v219, v60, v61
	v_mad_u32_u24 v40, v231, s29, v247
	s_and_saveexec_b64 s[30:31], s[14:15]
	global_store_dwordx2 v40, v[218:219], s[10:11] offset:8
	s_mov_b64 exec, s[30:31]
	v_mul_f32_e32 v208, 0xbfb8aa3b, v50
	v_mul_f32_e32 v209, 0xbfb8aa3b, v51
	v_mul_f32_e32 v210, 0xbfb8aa3b, v52
	v_mul_f32_e32 v211, 0xbfb8aa3b, v53
	v_exp_f32_e32 v208, v208
	v_exp_f32_e32 v209, v209
	v_exp_f32_e32 v210, v210
	v_exp_f32_e32 v211, v211
	v_add_f32_e32 v208, 1.0, v208
	v_add_f32_e32 v209, 1.0, v209
	v_add_f32_e32 v210, 1.0, v210
	v_add_f32_e32 v211, 1.0, v211
	v_rcp_f32_e32 v208, v208
	v_rcp_f32_e32 v209, v209
	v_rcp_f32_e32 v210, v210
	v_rcp_f32_e32 v211, v211
	v_mul_f32_e32 v50, v50, v208
	v_mul_f32_e32 v51, v51, v209
	v_mul_f32_e32 v52, v52, v210
	v_mul_f32_e32 v53, v53, v211
	v_mul_f32_e32 v50, v54, v50
	v_mul_f32_e32 v51, v55, v51
	v_mul_f32_e32 v52, v56, v52
	v_mul_f32_e32 v53, v57, v53
	v_cvt_pk_bf16_f32 v212, v50, v51
	v_cvt_pk_bf16_f32 v213, v52, v53
	v_mad_u32_u24 v221, v232, s29, v247
	s_and_saveexec_b64 s[30:31], s[16:17]
	global_store_dwordx2 v221, v[212:213], s[10:11] offset:8
	s_mov_b64 exec, s[30:31]
	v_mul_f32_e32 v208, 0xbfb8aa3b, v42
	v_mul_f32_e32 v209, 0xbfb8aa3b, v43
	v_mul_f32_e32 v210, 0xbfb8aa3b, v44
	v_mul_f32_e32 v211, 0xbfb8aa3b, v45
	v_exp_f32_e32 v208, v208
	v_exp_f32_e32 v209, v209
	v_exp_f32_e32 v210, v210
	v_exp_f32_e32 v211, v211
	v_add_f32_e32 v208, 1.0, v208
	v_add_f32_e32 v209, 1.0, v209
	v_add_f32_e32 v210, 1.0, v210
	v_add_f32_e32 v211, 1.0, v211
	v_rcp_f32_e32 v208, v208
	v_rcp_f32_e32 v209, v209
	v_rcp_f32_e32 v210, v210
	v_rcp_f32_e32 v211, v211
	v_mul_f32_e32 v42, v42, v208
	v_mul_f32_e32 v43, v43, v209
	v_mul_f32_e32 v44, v44, v210
	v_mul_f32_e32 v45, v45, v211
	v_mul_f32_e32 v42, v46, v42
	v_mul_f32_e32 v43, v47, v43
	v_mul_f32_e32 v44, v48, v44
	v_mul_f32_e32 v45, v49, v45
	v_cvt_pk_bf16_f32 v218, v42, v43
	v_cvt_pk_bf16_f32 v219, v44, v45
	v_mad_u32_u24 v40, v233, s29, v247
	s_and_saveexec_b64 s[30:31], s[18:19]
	global_store_dwordx2 v40, v[218:219], s[10:11] offset:8
	s_mov_b64 exec, s[30:31]
	ds_write_b64 v243, v[32:33]
	ds_write_b64 v243, v[24:25] offset:256
	ds_write_b64 v243, v[16:17] offset:512
	ds_write_b64 v243, v[8:9] offset:768
	s_waitcnt lgkmcnt(11)
; #define PG8_LAS __attribute__((address_space(3)))
; __device__ __forceinline__ float dpp_ror1(float v) { return __builtin_bit_cast(float, __builtin_amdgcn_update_dpp(0, __builtin_bit_cast(int, v), 0x121, 0xf, 0xf, false)); }
; __device__ __forceinline__ float dpp_ror15(float v) { return __builtin_bit_cast(float, __builtin_amdgcn_update_dpp(0, __builtin_bit_cast(int, v), 0x12F, 0xf, 0xf, false)); }
;     __device__ __forceinline__ void operator()(const f32x4 (&acc)[2][2][4][2], const Unit& u, int wr, int wc, int fr, int fq) const {
;     ...
;                     for (int bj = 0; bj < 2; ++bj) { const f32x4 cur = acc[ai][bj][m][n];
;                         f32x4 su = cur, sd = cur;
;                         if (m > 0) { if (fr == 15) su = acc[ai][bj][m > 0 ? m - 1 : 0][n]; }
;                         if (m < 3) { if (fr == 0) sd = acc[ai][bj][m < 3 ? m + 1 : 3][n]; }
;                         f32x4 up, dn;
;                         up[0] = dpp_ror1(su[0]); up[1] = dpp_ror1(su[1]); up[2] = dpp_ror1(su[2]); up[3] = dpp_ror1(su[3]);
;                         dn[0] = dpp_ror15(sd[0]); dn[1] = dpp_ror15(sd[1]); dn[2] = dpp_ror15(sd[2]); dn[3] = dpp_ror15(sd[3]);
;                         if (m == 0) { f32x4 halo = zero4; if (blk > 0) halo = *(const PG8_LAS f32x4*)(xb + (((((blk - 1) * 2 + 1) * 4 + wc) * 4 + fq) * 16 + (bj * 2 + n) * 4)); if (fr == 0) up = halo; }
;                         if (m == 3) { f32x4 halo = zero4; if (blk < 3) halo = *(const PG8_LAS f32x4*)(xb + (((((blk + 1) * 2 + 0) * 4 + wc) * 4 + fq) * 16 + (bj * 2 + n) * 4)); if (fr == 15) dn = halo; }
;                         if (edge) { if (!upok) up = zero4; if (!dnok) dn = zero4; }
;                         res[bj] = bb[bj] + w0[bj] * up + w1[bj] * cur + w2[bj] * dn; }
	v_cndmask_b32_e64 v170, v170, v198, s[6:7]
	v_cndmask_b32_e64 v171, v171, v199, s[6:7]
	v_pk_fma_f32 v[202:203], v[138:139], v[170:171], v[150:151]
	v_pk_fma_f32 v[30:31], v[30:31], v[142:143], v[202:203]
	v_pk_fma_f32 v[30:31], v[146:147], v[178:179], v[30:31]
	ds_read_b64 v[170:171], v244
	ds_read_b64 v[178:179], v243 offset:16
	ds_read_b64 v[198:199], v238 offset:3096
	s_waitcnt lgkmcnt(12)
	v_pk_fma_f32 v[202:203], v[138:139], v[172:173], v[150:151]
	v_pk_fma_f32 v[22:23], v[22:23], v[142:143], v[202:203]
	v_pk_fma_f32 v[22:23], v[146:147], v[180:181], v[22:23]
	ds_read_b64 v[172:173], v244 offset:256
	ds_read_b64 v[180:181], v243 offset:272
	s_waitcnt lgkmcnt(12)
	v_pk_fma_f32 v[202:203], v[138:139], v[174:175], v[150:151]
	v_pk_fma_f32 v[14:15], v[14:15], v[142:143], v[202:203]
	v_pk_fma_f32 v[14:15], v[146:147], v[194:195], v[14:15]
	ds_read_b64 v[174:175], v244 offset:512
	ds_read_b64 v[194:195], v243 offset:528
	s_waitcnt lgkmcnt(11)
	v_cndmask_b32_e64 v196, v196, v200, s[4:5]
	v_cndmask_b32_e64 v197, v197, v201, s[4:5]
	v_pk_fma_f32 v[202:203], v[138:139], v[176:177], v[150:151]
	v_pk_fma_f32 v[6:7], v[6:7], v[142:143], v[202:203]
	v_pk_fma_f32 v[6:7], v[146:147], v[196:197], v[6:7]
	ds_read_b64 v[176:177], v244 offset:768
	ds_read_b64 v[196:197], v243 offset:784
	ds_read_b64 v[200:201], v246 offset:24
	ds_write_b64 v243, v[26:27]
	ds_write_b64 v243, v[18:19] offset:256
	ds_write_b64 v243, v[10:11] offset:512
	ds_write_b64 v243, v[2:3] offset:768
	s_waitcnt lgkmcnt(11)
	v_cndmask_b32_e64 v170, v170, v198, s[6:7]
	v_cndmask_b32_e64 v171, v171, v199, s[6:7]
	v_pk_fma_f32 v[202:203], v[140:141], v[170:171], v[152:153]
	v_pk_fma_f32 v[32:33], v[32:33], v[144:145], v[202:203]
	v_pk_fma_f32 v[32:33], v[148:149], v[178:179], v[32:33]
	ds_read_b64 v[170:171], v244
	ds_read_b64 v[178:179], v243 offset:16
	ds_read_b64 v[198:199], v238 offset:3120
	s_waitcnt lgkmcnt(12)
	v_pk_fma_f32 v[202:203], v[140:141], v[172:173], v[152:153]
	v_pk_fma_f32 v[24:25], v[24:25], v[144:145], v[202:203]
	v_pk_fma_f32 v[24:25], v[148:149], v[180:181], v[24:25]
	ds_read_b64 v[172:173], v244 offset:256
	ds_read_b64 v[180:181], v243 offset:272
	s_waitcnt lgkmcnt(12)
	v_pk_fma_f32 v[202:203], v[140:141], v[174:175], v[152:153]
	v_pk_fma_f32 v[16:17], v[16:17], v[144:145], v[202:203]
	v_pk_fma_f32 v[16:17], v[148:149], v[194:195], v[16:17]
	ds_read_b64 v[174:175], v244 offset:512
	ds_read_b64 v[194:195], v243 offset:528
	s_waitcnt lgkmcnt(11)
	v_cndmask_b32_e64 v196, v196, v200, s[4:5]
	v_cndmask_b32_e64 v197, v197, v201, s[4:5]
	v_pk_fma_f32 v[202:203], v[140:141], v[176:177], v[152:153]
	v_pk_fma_f32 v[8:9], v[8:9], v[144:145], v[202:203]
	v_pk_fma_f32 v[8:9], v[148:149], v[196:197], v[8:9]
	ds_read_b64 v[176:177], v244 offset:768
	ds_read_b64 v[196:197], v243 offset:784
	ds_read_b64 v[200:201], v246 offset:48
	ds_write_b64 v243, v[28:29]
	ds_write_b64 v243, v[20:21] offset:256
	ds_write_b64 v243, v[12:13] offset:512
	ds_write_b64 v243, v[4:5] offset:768
	s_waitcnt lgkmcnt(11)
	v_cndmask_b32_e64 v170, v170, v198, s[6:7]
	v_cndmask_b32_e64 v171, v171, v199, s[6:7]
	v_pk_fma_f32 v[202:203], v[154:155], v[170:171], v[166:167]
	v_pk_fma_f32 v[26:27], v[26:27], v[158:159], v[202:203]
	v_pk_fma_f32 v[26:27], v[162:163], v[178:179], v[26:27]
	ds_read_b64 v[170:171], v244
	ds_read_b64 v[178:179], v243 offset:16
	ds_read_b64 v[198:199], v238 offset:3128
	s_waitcnt lgkmcnt(12)
	v_pk_fma_f32 v[202:203], v[154:155], v[172:173], v[166:167]
	v_pk_fma_f32 v[18:19], v[18:19], v[158:159], v[202:203]
	v_pk_fma_f32 v[18:19], v[162:163], v[180:181], v[18:19]
	ds_read_b64 v[172:173], v244 offset:256
	ds_read_b64 v[180:181], v243 offset:272
	s_waitcnt lgkmcnt(12)
	v_pk_fma_f32 v[202:203], v[154:155], v[174:175], v[166:167]
	v_pk_fma_f32 v[10:11], v[10:11], v[158:159], v[202:203]
	v_pk_fma_f32 v[10:11], v[162:163], v[194:195], v[10:11]
	ds_read_b64 v[174:175], v244 offset:512
	ds_read_b64 v[194:195], v243 offset:528
	s_waitcnt lgkmcnt(11)
	v_cndmask_b32_e64 v196, v196, v200, s[4:5]
	v_cndmask_b32_e64 v197, v197, v201, s[4:5]
	v_pk_fma_f32 v[202:203], v[154:155], v[176:177], v[166:167]
	v_pk_fma_f32 v[2:3], v[2:3], v[158:159], v[202:203]
	v_pk_fma_f32 v[2:3], v[162:163], v[196:197], v[2:3]
	ds_read_b64 v[176:177], v244 offset:768
	ds_read_b64 v[196:197], v243 offset:784
	ds_read_b64 v[200:201], v246 offset:56
	s_waitcnt lgkmcnt(7)
	v_cndmask_b32_e64 v170, v170, v198, s[6:7]
	v_cndmask_b32_e64 v171, v171, v199, s[6:7]
	v_pk_fma_f32 v[202:203], v[156:157], v[170:171], v[168:169]
	v_pk_fma_f32 v[28:29], v[28:29], v[160:161], v[202:203]
	v_pk_fma_f32 v[28:29], v[164:165], v[178:179], v[28:29]
	s_waitcnt lgkmcnt(5)
; __device__ __forceinline__ unsigned cvt_pk_bf16(float lo, float hi) { unsigned r; asm volatile("v_cvt_pk_bf16_f32 %0, %1, %2" : "=v"(r) : "v"(lo), "v"(hi)); return r; }
;     __device__ __forceinline__ void operator()(const f32x4 (&acc)[2][2][4][2], const Unit& u, int wr, int wc, int fr, int fq) const {
;     ...
;                     if (store_ok) {
;                         float o[4];
; #pragma unroll
;                         for (int j = 0; j < 4; ++j) { const float gg = res[1][j]; o[j] = gg * __builtin_amdgcn_rcpf(1.f + __expf(-gg)) * res[0][j]; }
;                         u32x2 w; w.x = cvt_pk_bf16(o[0], o[1]); w.y = cvt_pk_bf16(o[2], o[3]);
;                         *(u32x2*)(ACT + (size_t)(seqrow + t) * 2816 + ch0 + 4 * n) = w; } } }
	v_pk_fma_f32 v[202:203], v[156:157], v[172:173], v[168:169]
	v_pk_fma_f32 v[20:21], v[20:21], v[160:161], v[202:203]
	v_pk_fma_f32 v[20:21], v[164:165], v[180:181], v[20:21]
	s_waitcnt lgkmcnt(3)
	v_pk_fma_f32 v[202:203], v[156:157], v[174:175], v[168:169]
	v_pk_fma_f32 v[12:13], v[12:13], v[160:161], v[202:203]
	v_pk_fma_f32 v[12:13], v[164:165], v[194:195], v[12:13]
	s_waitcnt lgkmcnt(0)
	v_cndmask_b32_e64 v196, v196, v200, s[4:5]
	v_cndmask_b32_e64 v197, v197, v201, s[4:5]
	v_pk_fma_f32 v[202:203], v[156:157], v[176:177], v[168:169]
	v_pk_fma_f32 v[4:5], v[4:5], v[160:161], v[202:203]
	v_pk_fma_f32 v[4:5], v[164:165], v[196:197], v[4:5]
	v_mul_f32_e32 v208, 0xbfb8aa3b, v26
	v_mul_f32_e32 v209, 0xbfb8aa3b, v27
	v_mul_f32_e32 v210, 0xbfb8aa3b, v28
	v_mul_f32_e32 v211, 0xbfb8aa3b, v29
	v_exp_f32_e32 v208, v208
	v_exp_f32_e32 v209, v209
	v_exp_f32_e32 v210, v210
	v_exp_f32_e32 v211, v211
	v_add_f32_e32 v208, 1.0, v208
	v_add_f32_e32 v209, 1.0, v209
	v_add_f32_e32 v210, 1.0, v210
	v_add_f32_e32 v211, 1.0, v211
	v_rcp_f32_e32 v208, v208
	v_rcp_f32_e32 v209, v209
	v_rcp_f32_e32 v210, v210
	v_rcp_f32_e32 v211, v211
	v_mul_f32_e32 v26, v26, v208
	v_mul_f32_e32 v27, v27, v209
	v_mul_f32_e32 v28, v28, v210
	v_mul_f32_e32 v29, v29, v211
	v_mul_f32_e32 v26, v30, v26
	v_mul_f32_e32 v27, v31, v27
	v_mul_f32_e32 v28, v32, v28
	v_mul_f32_e32 v29, v33, v29
	v_cvt_pk_bf16_f32 v212, v26, v27
	v_cvt_pk_bf16_f32 v213, v28, v29
	v_mad_u32_u24 v221, v234, s29, v247
	s_and_saveexec_b64 s[30:31], s[20:21]
	global_store_dwordx2 v221, v[212:213], s[10:11] offset:8
	s_mov_b64 exec, s[30:31]
	v_mul_f32_e32 v208, 0xbfb8aa3b, v18
	v_mul_f32_e32 v209, 0xbfb8aa3b, v19
	v_mul_f32_e32 v210, 0xbfb8aa3b, v20
	v_mul_f32_e32 v211, 0xbfb8aa3b, v21
	v_exp_f32_e32 v208, v208
	v_exp_f32_e32 v209, v209
	v_exp_f32_e32 v210, v210
	v_exp_f32_e32 v211, v211
	v_add_f32_e32 v208, 1.0, v208
	v_add_f32_e32 v209, 1.0, v209
	v_add_f32_e32 v210, 1.0, v210
	v_add_f32_e32 v211, 1.0, v211
	v_rcp_f32_e32 v208, v208
	v_rcp_f32_e32 v209, v209
	v_rcp_f32_e32 v210, v210
	v_rcp_f32_e32 v211, v211
	v_mul_f32_e32 v18, v18, v208
	v_mul_f32_e32 v19, v19, v209
	v_mul_f32_e32 v20, v20, v210
	v_mul_f32_e32 v21, v21, v211
	v_mul_f32_e32 v18, v22, v18
	v_mul_f32_e32 v19, v23, v19
	v_mul_f32_e32 v20, v24, v20
	v_mul_f32_e32 v21, v25, v21
	v_cvt_pk_bf16_f32 v218, v18, v19
	v_cvt_pk_bf16_f32 v219, v20, v21
	v_mad_u32_u24 v40, v235, s29, v247
	s_and_saveexec_b64 s[30:31], s[22:23]
	global_store_dwordx2 v40, v[218:219], s[10:11] offset:8
	s_mov_b64 exec, s[30:31]
	v_mul_f32_e32 v208, 0xbfb8aa3b, v10
	v_mul_f32_e32 v209, 0xbfb8aa3b, v11
	v_mul_f32_e32 v210, 0xbfb8aa3b, v12
	v_mul_f32_e32 v211, 0xbfb8aa3b, v13
	v_exp_f32_e32 v208, v208
	v_exp_f32_e32 v209, v209
	v_exp_f32_e32 v210, v210
	v_exp_f32_e32 v211, v211
	v_add_f32_e32 v208, 1.0, v208
	v_add_f32_e32 v209, 1.0, v209
	v_add_f32_e32 v210, 1.0, v210
	v_add_f32_e32 v211, 1.0, v211
	v_rcp_f32_e32 v208, v208
	v_rcp_f32_e32 v209, v209
	v_rcp_f32_e32 v210, v210
	v_rcp_f32_e32 v211, v211
	v_mul_f32_e32 v10, v10, v208
	v_mul_f32_e32 v11, v11, v209
	v_mul_f32_e32 v12, v12, v210
	v_mul_f32_e32 v13, v13, v211
	v_mul_f32_e32 v10, v14, v10
	v_mul_f32_e32 v11, v15, v11
	v_mul_f32_e32 v12, v16, v12
	v_mul_f32_e32 v13, v17, v13
	v_cvt_pk_bf16_f32 v212, v10, v11
	v_cvt_pk_bf16_f32 v213, v12, v13
	v_mad_u32_u24 v221, v236, s29, v247
	s_and_saveexec_b64 s[30:31], s[24:25]
	global_store_dwordx2 v221, v[212:213], s[10:11] offset:8
	s_mov_b64 exec, s[30:31]
	v_mul_f32_e32 v208, 0xbfb8aa3b, v2
	v_mul_f32_e32 v209, 0xbfb8aa3b, v3
	v_mul_f32_e32 v210, 0xbfb8aa3b, v4
	v_mul_f32_e32 v211, 0xbfb8aa3b, v5
	v_exp_f32_e32 v208, v208
	v_exp_f32_e32 v209, v209
	v_exp_f32_e32 v210, v210
	v_exp_f32_e32 v211, v211
	v_add_f32_e32 v208, 1.0, v208
	v_add_f32_e32 v209, 1.0, v209
	v_add_f32_e32 v210, 1.0, v210
	v_add_f32_e32 v211, 1.0, v211
	v_rcp_f32_e32 v208, v208
	v_rcp_f32_e32 v209, v209
	v_rcp_f32_e32 v210, v210
	v_rcp_f32_e32 v211, v211
	v_mul_f32_e32 v2, v2, v208
	v_mul_f32_e32 v3, v3, v209
	v_mul_f32_e32 v4, v4, v210
	v_mul_f32_e32 v5, v5, v211
	v_mul_f32_e32 v2, v6, v2
	v_mul_f32_e32 v3, v7, v3
	v_mul_f32_e32 v4, v8, v4
	v_mul_f32_e32 v5, v9, v5
	v_cvt_pk_bf16_f32 v218, v2, v3
	v_cvt_pk_bf16_f32 v219, v4, v5
	v_mad_u32_u24 v40, v237, s29, v247
	s_and_saveexec_b64 s[30:31], s[26:27]
	global_store_dwordx2 v40, v[218:219], s[10:11] offset:8
	s_mov_b64 exec, s[30:31]
	s_branch .Lec_done
	s_nop 0
